# ssm pass1 group loop rewritten by hand (transposed tile, b128 reads, fmac scan, pipelined next-group MFMAs)
# speedup vs baseline: 1.0028x; 1.0028x over previous
; #define LAS __attribute__((address_space(3)))
; __device__ __forceinline__ void ssm_ops_load(SsmOps& S, const float* ABAR, const bf16_t* BBH, const bf16_t* BBL, int g, int lane) {
;     ...
;     for (int nb = 0; nb < 8; ++nb) { const size_t o = (size_t)(g * 128 + 16 * nb + fr) * 16 + (fq & 1) * 8;
;         const bf16x8 h = *(const bf16x8*)(BBH + o); S.bh[nb] = fq < 2 ? h : z; }
;     S.ar = ABAR[2 * (g * 64 + lane)]; S.ai = ABAR[2 * (g * 64 + lane) + 1];
; }
; __device__ __forceinline__ void ssm_bu_tile(const SsmOps& S, bf16x8 uh, LAS float* tile, int lane) {
;     const int fr = lane & 15, fq = lane >> 4;
;     if (fq >= 2) uh = (bf16x8){0, 0, 0, 0, 0, 0, 0, 0};
; #pragma unroll
;     for (int nb = 0; nb < 8; ++nb) { f32x4 acc = {0.f, 0.f, 0.f, 0.f};
;         acc = __builtin_amdgcn_mfma_f32_16x16x32_bf16(S.bh[nb], uh, acc, 0, 0, 0);
;         *(LAS f32x4*)(tile + fr * TSTR + 16 * nb + 4 * fq) = acc; }
; __device__ __forceinline__ void ssm_pass1(LAS unsigned char* lds, const bf16_t* US, float* SST, const float* ABAR, const bf16_t* BBH, const bf16_t* BBL, int gw, int NGW, int lane, int wave) {
;     ...
;         const int c = idx % 7, bg = idx / 7, b = bg >> 5, g = bg & 31;
;         SsmOps S; ssm_ops_load(S, ABAR, BBH, BBL, g, lane);
;         float xr = 0.f, xi = 0.f; const int tokc = b * SEQ + c * 256;
;         bf16x8 uh; ssm_u_load(uh, US, tokc, g, lane);
;         for (int grp = 0; grp < 16; ++grp) {
;             ssm_bu_tile(S, uh, tile, lane);
;             if (grp < 15) ssm_u_load(uh, US, tokc + (grp + 1) * 16, g, lane);
.LBB0_487:
	s_mul_hi_i32 s12, s3, 0x92492493
	s_add_i32 s12, s12, s3
	s_lshr_b32 s14, s12, 31
	s_ashr_i32 s12, s12, 2
	s_add_i32 s14, s12, s14
	s_mul_i32 s15, s14, 7
	s_lshl_b32 s17, s14, 6
	s_sub_i32 s16, s3, s15
	s_and_b32 s12, s14, 31
	s_and_b32 s15, s17, 0xfffff800
	s_lshl_b32 s17, s16, 8
	v_lshl_or_b32 v0, s12, 12, v52
	v_lshl_or_b32 v1, s12, 9, v53
	s_add_i32 s17, s15, s17
	global_load_dwordx2 v[40:41], v1, s[0:1]
	global_load_dwordx4 v[4:7], v0, s[10:11]
	global_load_dwordx4 v[8:11], v0, s[10:11] offset:512
	global_load_dwordx4 v[12:15], v0, s[10:11] offset:1024
	global_load_dwordx4 v[16:19], v0, s[10:11] offset:1536
	global_load_dwordx4 v[20:23], v0, s[10:11] offset:2048
	global_load_dwordx4 v[24:27], v0, s[10:11] offset:2560
	global_load_dwordx4 v[56:59], v0, s[10:11] offset:3072
	global_load_dwordx4 v[60:63], v0, s[10:11] offset:3584
	v_or_b32_e32 v0, s17, v48
	v_ashrrev_i32_e32 v1, 31, v0
	v_lshlrev_b64 v[0:1], 10, v[0:1]
	s_lshl_b32 s12, s12, 5
	v_lshl_add_u64 v[0:1], s[46:47], 0, v[0:1]
	v_lshl_add_u64 v[0:1], v[0:1], 0, s[12:13]
	v_lshl_add_u64 v[0:1], v[0:1], 0, v[36:37]
	global_load_dwordx4 v[0:3], v[0:1], off
	v_lshl_add_u64 v[42:43], v[38:39], 0, s[12:13]
	s_lshl_b32 s12, s3, 8
	s_add_i32 s12, s12, s15
	v_or_b32_e32 v46, s12, v51
	s_mul_i32 s12, s14, 0x700
	v_subrev_u32_e32 v55, s12, v46
	s_mov_b32 s12, 0
	v_mov_b32_e32 v46, 0
	v_mov_b32_e32 v47, v37
	s_waitcnt vmcnt(0)
	v_pk_mov_b32 v[44:45], v[40:41], v[40:41] op_sel:[1,0]
	v_cndmask_b32_e32 v7, 0, v7, vcc
	v_cndmask_b32_e32 v6, 0, v6, vcc
	v_cndmask_b32_e32 v5, 0, v5, vcc
	v_cndmask_b32_e32 v4, 0, v4, vcc
	v_cndmask_b32_e32 v11, 0, v11, vcc
	v_cndmask_b32_e32 v10, 0, v10, vcc
	v_cndmask_b32_e32 v9, 0, v9, vcc
	v_cndmask_b32_e32 v8, 0, v8, vcc
	v_cndmask_b32_e32 v15, 0, v15, vcc
	v_cndmask_b32_e32 v14, 0, v14, vcc
	v_cndmask_b32_e32 v13, 0, v13, vcc
	v_cndmask_b32_e32 v12, 0, v12, vcc
	v_cndmask_b32_e32 v19, 0, v19, vcc
	v_cndmask_b32_e32 v18, 0, v18, vcc
	v_cndmask_b32_e32 v17, 0, v17, vcc
	v_cndmask_b32_e32 v16, 0, v16, vcc
	v_cndmask_b32_e32 v31, 0, v23, vcc
	v_cndmask_b32_e32 v30, 0, v22, vcc
	v_cndmask_b32_e32 v29, 0, v21, vcc
	v_cndmask_b32_e32 v28, 0, v20, vcc
	v_cndmask_b32_e32 v35, 0, v27, vcc
	v_cndmask_b32_e32 v34, 0, v26, vcc
	v_cndmask_b32_e32 v33, 0, v25, vcc
	v_cndmask_b32_e32 v32, 0, v24, vcc
	v_cndmask_b32_e32 v27, 0, v59, vcc
	v_cndmask_b32_e32 v26, 0, v58, vcc
	v_cndmask_b32_e32 v25, 0, v57, vcc
	v_cndmask_b32_e32 v24, 0, v56, vcc
	v_cndmask_b32_e32 v23, 0, v63, vcc
	v_cndmask_b32_e32 v22, 0, v62, vcc
	v_cndmask_b32_e32 v21, 0, v61, vcc
	v_cndmask_b32_e32 v20, 0, v60, vcc
	v_readlane_b32 s98, v249, 18
	s_mov_b32 s100, 0x4000
	s_mov_b32 s101, 0
	s_mov_b32 s12, 0
	s_mul_i32 s98, s98, 0x2800
	s_add_i32 s98, s98, 0x8000
	v_lshrrev_b32_e32 v109, 4, v196
	v_mul_u32_u24_e32 v144, 0x50, v48
	v_lshl_add_u32 v144, v109, 4, v144
	v_add_u32_e32 v144, s98, v144
	v_mul_u32_u24_e32 v145, 0x50, v196
	v_add_u32_e32 v145, s98, v145
	v_xor_b32_e32 v77, 0x80000000, v41
	v_mov_b32_e32 v100, 0
	v_mov_b32_e32 v76, 0
	v_lshlrev_b32_e32 v112, 10, v55
	v_mov_b32_e32 v113, 0
	v_lshl_add_u64 v[148:149], v[42:43], 0, v[112:113]
	v_cndmask_b32_e64 v235, v3, 0, s[4:5]
	v_cndmask_b32_e64 v234, v2, 0, s[4:5]
	v_cndmask_b32_e64 v233, v1, 0, s[4:5]
	v_cndmask_b32_e64 v232, v0, 0, s[4:5]
	global_load_dwordx4 v[0:3], v[148:149], off
	v_lshl_add_u64 v[148:149], v[148:149], 0, s[100:101]
	v_mfma_f32_16x16x32_bf16 v[160:163], v[232:235], v[4:7], 0
	v_mfma_f32_16x16x32_bf16 v[164:167], v[232:235], v[8:11], 0
	v_mfma_f32_16x16x32_bf16 v[168:171], v[232:235], v[12:15], 0
	v_mfma_f32_16x16x32_bf16 v[172:175], v[232:235], v[16:19], 0
	v_mfma_f32_16x16x32_bf16 v[176:179], v[232:235], v[28:31], 0
	v_mfma_f32_16x16x32_bf16 v[180:183], v[232:235], v[32:35], 0
	v_mfma_f32_16x16x32_bf16 v[184:187], v[232:235], v[24:27], 0
	v_mfma_f32_16x16x32_bf16 v[188:191], v[232:235], v[20:23], 0
	s_nop 0
	ds_write_b128 v144, v[160:163]
	ds_write_b128 v144, v[164:167] offset:1280
	ds_write_b128 v144, v[168:171] offset:2560
	ds_write_b128 v144, v[172:175] offset:3840
	ds_write_b128 v144, v[176:179] offset:5120
	ds_write_b128 v144, v[180:183] offset:6400
	ds_write_b128 v144, v[184:187] offset:7680
	ds_write_b128 v144, v[188:191] offset:8960
; #define LAS __attribute__((address_space(3)))
; __device__ __forceinline__ void ssm_bu_tile(const SsmOps& S, bf16x8 uh, LAS float* tile, int lane) {
;     ...
;     if (fq >= 2) uh = (bf16x8){0, 0, 0, 0, 0, 0, 0, 0};
; #pragma unroll
;     for (int nb = 0; nb < 8; ++nb) { f32x4 acc = {0.f, 0.f, 0.f, 0.f};
;         acc = __builtin_amdgcn_mfma_f32_16x16x32_bf16(S.bh[nb], uh, acc, 0, 0, 0);
;         *(LAS f32x4*)(tile + fr * TSTR + 16 * nb + 4 * fq) = acc; }
; __device__ __forceinline__ void ssm_pass1(LAS unsigned char* lds, const bf16_t* US, float* SST, const float* ABAR, const bf16_t* BBH, const bf16_t* BBL, int gw, int NGW, int lane, int wave) {
;     ...
;         for (int grp = 0; grp < 16; ++grp) {
;             ssm_bu_tile(S, uh, tile, lane);
;             if (grp < 15) ssm_u_load(uh, US, tokc + (grp + 1) * 16, g, lane);
;             float br[16], bi[16];
; #pragma unroll
;             for (int t = 0; t < 16; ++t) { br[t] = tile[t * TSTR + lane]; bi[t] = tile[t * TSTR + 64 + lane]; }
;             asm volatile("s_waitcnt lgkmcnt(0)" ::: "memory");
; #pragma unroll
;             for (int t = 0; t < 16; ++t) { const float nr = S.ar * xr - S.ai * xi + br[t], ni = S.ar * xi + S.ai * xr + bi[t]; xr = nr; xi = ni; }
;         }
;         float* so = SST + ((size_t)bg * 8 + c) * 128; so[lane] = xr; so[64 + lane] = xi;
.Lssm1_grp:
	s_waitcnt lgkmcnt(0)
	ds_read_b128 v[200:203], v145
	ds_read_b128 v[216:219], v145 offset:5120
	ds_read_b128 v[204:207], v145 offset:16
	ds_read_b128 v[220:223], v145 offset:5136
	ds_read_b128 v[208:211], v145 offset:32
	ds_read_b128 v[224:227], v145 offset:5152
	ds_read_b128 v[212:215], v145 offset:48
	ds_read_b128 v[228:231], v145 offset:5168
	s_waitcnt vmcnt(0)
	v_cndmask_b32_e64 v235, v3, 0, s[4:5]
	v_cndmask_b32_e64 v234, v2, 0, s[4:5]
	v_cndmask_b32_e64 v233, v1, 0, s[4:5]
	v_cndmask_b32_e64 v232, v0, 0, s[4:5]
	s_cmp_ge_u32 s12, 14
	s_cbranch_scc1 .Lssm1_noload
	global_load_dwordx4 v[0:3], v[148:149], off
	v_lshl_add_u64 v[148:149], v[148:149], 0, s[100:101]
.Lssm1_noload:
	v_mfma_f32_16x16x32_bf16 v[160:163], v[232:235], v[4:7], 0
	v_mfma_f32_16x16x32_bf16 v[164:167], v[232:235], v[8:11], 0
	v_mfma_f32_16x16x32_bf16 v[168:171], v[232:235], v[12:15], 0
	v_mfma_f32_16x16x32_bf16 v[172:175], v[232:235], v[16:19], 0
	v_mfma_f32_16x16x32_bf16 v[176:179], v[232:235], v[28:31], 0
	v_mfma_f32_16x16x32_bf16 v[180:183], v[232:235], v[32:35], 0
	v_mfma_f32_16x16x32_bf16 v[184:187], v[232:235], v[24:27], 0
	v_mfma_f32_16x16x32_bf16 v[188:191], v[232:235], v[20:23], 0
	s_waitcnt lgkmcnt(6)
	v_fmac_f32_e32 v200, v40, v100
	v_fmac_f32_e32 v216, v40, v76
	v_fmac_f32_e32 v200, v77, v76
	v_fmac_f32_e32 v216, v41, v100
	v_fmac_f32_e32 v201, v40, v200
	v_fmac_f32_e32 v217, v40, v216
	v_fmac_f32_e32 v201, v77, v216
	v_fmac_f32_e32 v217, v41, v200
	v_fmac_f32_e32 v202, v40, v201
	v_fmac_f32_e32 v218, v40, v217
	v_fmac_f32_e32 v202, v77, v217
	v_fmac_f32_e32 v218, v41, v201
	v_fmac_f32_e32 v203, v40, v202
	v_fmac_f32_e32 v219, v40, v218
	v_fmac_f32_e32 v203, v77, v218
	v_fmac_f32_e32 v219, v41, v202
	s_waitcnt lgkmcnt(4)
	v_fmac_f32_e32 v204, v40, v203
	v_fmac_f32_e32 v220, v40, v219
	v_fmac_f32_e32 v204, v77, v219
	v_fmac_f32_e32 v220, v41, v203
	v_fmac_f32_e32 v205, v40, v204
	v_fmac_f32_e32 v221, v40, v220
	v_fmac_f32_e32 v205, v77, v220
	v_fmac_f32_e32 v221, v41, v204
	v_fmac_f32_e32 v206, v40, v205
	v_fmac_f32_e32 v222, v40, v221
	v_fmac_f32_e32 v206, v77, v221
	v_fmac_f32_e32 v222, v41, v205
	v_fmac_f32_e32 v207, v40, v206
	v_fmac_f32_e32 v223, v40, v222
	v_fmac_f32_e32 v207, v77, v222
	v_fmac_f32_e32 v223, v41, v206
	s_waitcnt lgkmcnt(2)
	v_fmac_f32_e32 v208, v40, v207
	v_fmac_f32_e32 v224, v40, v223
	v_fmac_f32_e32 v208, v77, v223
	v_fmac_f32_e32 v224, v41, v207
	v_fmac_f32_e32 v209, v40, v208
	v_fmac_f32_e32 v225, v40, v224
	v_fmac_f32_e32 v209, v77, v224
	v_fmac_f32_e32 v225, v41, v208
	v_fmac_f32_e32 v210, v40, v209
	v_fmac_f32_e32 v226, v40, v225
	v_fmac_f32_e32 v210, v77, v225
	v_fmac_f32_e32 v226, v41, v209
	v_fmac_f32_e32 v211, v40, v210
	v_fmac_f32_e32 v227, v40, v226
	v_fmac_f32_e32 v211, v77, v226
	v_fmac_f32_e32 v227, v41, v210
	s_waitcnt lgkmcnt(0)
	v_fmac_f32_e32 v212, v40, v211
	v_fmac_f32_e32 v228, v40, v227
	v_fmac_f32_e32 v212, v77, v227
	v_fmac_f32_e32 v228, v41, v211
	v_fmac_f32_e32 v213, v40, v212
	v_fmac_f32_e32 v229, v40, v228
	v_fmac_f32_e32 v213, v77, v228
	v_fmac_f32_e32 v229, v41, v212
	v_fmac_f32_e32 v214, v40, v213
	v_fmac_f32_e32 v230, v40, v229
	v_fmac_f32_e32 v214, v77, v229
	v_fmac_f32_e32 v230, v41, v213
	v_fmac_f32_e32 v215, v40, v214
	v_fmac_f32_e32 v231, v40, v230
	v_fmac_f32_e32 v215, v77, v230
	v_fmac_f32_e32 v231, v41, v214
	v_mov_b32_e32 v100, v215
	v_mov_b32_e32 v76, v231
	ds_write_b128 v144, v[160:163]
	ds_write_b128 v144, v[164:167] offset:1280
	ds_write_b128 v144, v[168:171] offset:2560
	ds_write_b128 v144, v[172:175] offset:3840
	ds_write_b128 v144, v[176:179] offset:5120
	ds_write_b128 v144, v[180:183] offset:6400
	ds_write_b128 v144, v[184:187] offset:7680
	ds_write_b128 v144, v[188:191] offset:8960
	s_add_i32 s12, s12, 1
	s_cmp_eq_u32 s12, 16
	s_cbranch_scc0 .Lssm1_grp
	s_waitcnt vmcnt(0)
	s_ashr_i32 s15, s14, 31
	s_ashr_i32 s17, s16, 31
	s_lshl_b64 s[14:15], s[14:15], 12
	s_add_u32 s12, s6, s14
	s_addc_u32 s18, s7, s15
	s_lshl_b64 s[14:15], s[16:17], 9
	s_add_u32 s14, s12, s14
	s_addc_u32 s15, s18, s15
	global_store_dword v54, v100, s[14:15]
	global_store_dword v54, v76, s[14:15] offset:256
	s_waitcnt lgkmcnt(0)
	s_add_i32 s3, s3, s33
	s_cmpk_gt_i32 s3, 0xdff
	s_cbranch_scc0 .LBB0_487
